# v112 + E2 readiness poll per wave, overlapped with the tile prologue loads (off the ticket path)
# speedup vs baseline: 1.0048x; 1.0048x over previous
; template <bool ABF, bool BBF, class RowF, class ColF, class Epi>
; __device__ __forceinline__ void gemm_tile(char* smem, int K, RowF rowptr, ColF colptr, int ldb, Epi epi) {
;     ...
;   auto gload = [&](int k0) {
; #pragma unroll
;     for (int i = 0; i < NA; i++) ra[i] = *(const u32x4*)(ap[i] + (size_t)k0 * (ABF ? 2 : 4));
;     if (BBF) {
; #pragma unroll
;       for (int i = 0; i < 4; i++) rbb[BBF ? i : 0] = *(const u32x4*)(bq[i] + (size_t)k0 * 2);
;     } else {
;       const float* b = bp + (size_t)k0 * ldb;
; #pragma unroll
;       for (int j = 0; j < 32; j++) rb[BBF ? 0 : j] = b[(size_t)j * ldb];
;     }
; __device__ void phaseE2(const Params& p, char* smem) {
;     ...
;   xcd_queue_run(p.bar + QW_BASE + 1536, s_rb[NEXP], smem + 2 * GEMM_SMEM + 800, [&](int j, int q) {
;     const int rbg = q, nt = j;
;     int e = 0;
;     while (s_rb[e + 1] <= rbg) e++;
;     const int rb = rbg - s_rb[e];
;     const int cnt = p.cnt[e];
;     const int rows = min(128, cnt - rb * 128);
;     const int slot0 = s_off[e] + rb * 128;
;     const int n0 = nt * 128;
;     const float* wd = p.w_down + (size_t)e * DEXP * DM;
;     const float* lg = p.list_gate + e * CAP + rb * 128;
;     auto rowf = [&](int r) { int rr = r < rows ? r : 0; return (const void*)(p.H + (size_t)(slot0 + rr) * DEXP); };
;     auto colf = [&](int c) { return (const void*)(wd + n0 + c); };
.LBB0_1355:
	s_or_b64 exec, exec, s[16:17]
	s_cmp_lg_u32 s33, -1
	s_cselect_b32 s2, s33, 0
	s_cselect_b32 s16, s1, 0
	v_mov_b32_e32 v0, s2
	v_mov_b32_e32 v1, s16
	s_waitcnt lgkmcnt(0)
	s_barrier
	flat_load_dword v2, v[0:1] sc0 sc1
	s_waitcnt vmcnt(0)
	s_mov_b64 s[18:19], -1
	s_waitcnt lgkmcnt(0)
	v_cmp_lt_i32_e32 vcc, v2, v108
	s_and_saveexec_b64 s[16:17], vcc
	s_cbranch_execz .LBB0_1350
	v_lshrrev_b32_e32 v236, 5, v2
	v_lshlrev_b32_e32 v236, 8, v236
	v_and_b32_e32 v237, 31, v2
	v_lshl_add_u32 v236, v237, 2, v236
	v_add_u32_e32 v236, 0x4604, v236
	global_load_dword v237, v236, s[82:83] sc1
	s_mov_b64 s[18:19], 0
	v_mbcnt_lo_u32_b32 v3, -1, 0
	v_mbcnt_hi_u32_b32 v3, -1, v3
	v_lshl_add_u32 v3, v3, 2, s24
	ds_read_b32 v3, v3
	s_waitcnt lgkmcnt(0)
	v_cmp_le_i32_e32 vcc, v3, v2
	s_bcnt1_i32_b64 s2, vcc
	v_mov_b32_e32 v80, s2
	s_lshl_b32 s20, s2, 21
	s_mov_b32 s21, 0
	v_lshl_add_u64 v[96:97], v[90:91], 0, s[20:21]
	s_or_b64 exec, exec, s[18:19]
	v_mul_u32_u24_e32 v0, 0x20100, v80
	v_mov_b32_e32 v1, 0
	v_lshl_add_u64 v[0:1], v[0:1], 0, s[62:63]
	global_load_dword v3, v[0:1], off
	v_lshl_add_u32 v4, v80, 2, 0
	v_lshlrev_b64 v[0:1], 21, v[80:81]
	v_add_u32_e32 v5, 0x10120, v4
	v_add_u32_e32 v4, 0x10000, v4
	v_lshl_add_u64 v[0:1], v[92:93], 0, v[0:1]
	ds_read_b32 v22, v5
	ds_read_b32 v23, v4
	v_add_co_u32_e32 v4, vcc, s26, v0
	v_mov_b32_e32 v64, 0
	s_nop 0
	v_addc_co_u32_e32 v5, vcc, 0, v1, vcc
	v_add_co_u32_e32 v6, vcc, s27, v0
	s_waitcnt lgkmcnt(1)
	v_sub_u32_e32 v2, v2, v22
	v_addc_co_u32_e32 v7, vcc, 0, v1, vcc
	v_add_co_u32_e32 v8, vcc, s28, v0
	v_lshlrev_b32_e32 v98, 7, v2
	s_nop 0
	v_addc_co_u32_e32 v9, vcc, 0, v1, vcc
	v_add_co_u32_e32 v10, vcc, s29, v0
	s_waitcnt lgkmcnt(0)
	v_add_u32_e32 v117, v23, v98
	v_addc_co_u32_e32 v11, vcc, 0, v1, vcc
	v_add_co_u32_e32 v12, vcc, s30, v0
	s_mov_b32 s2, 0
	s_nop 0
	v_addc_co_u32_e32 v13, vcc, 0, v1, vcc
	v_add_co_u32_e32 v14, vcc, s31, v0
	s_mov_b32 s47, 0
	s_nop 0
	v_addc_co_u32_e32 v15, vcc, 0, v1, vcc
	v_add_co_u32_e32 v16, vcc, s36, v0
	v_mov_b32_e32 v65, v64
	s_nop 0
	v_addc_co_u32_e32 v17, vcc, 0, v1, vcc
	v_add_co_u32_e32 v18, vcc, s25, v0
	global_load_dword v141, v[0:1], off
	global_load_dword v99, v[4:5], off offset:-4096
	global_load_dword v119, v[4:5], off
	global_load_dword v120, v[6:7], off offset:-4096
	global_load_dword v121, v[6:7], off
	global_load_dword v122, v[8:9], off offset:-4096
	global_load_dword v123, v[8:9], off
	global_load_dword v128, v[10:11], off offset:-4096
	global_load_dword v130, v[10:11], off
	global_load_dword v132, v[12:13], off offset:-4096
	global_load_dword v133, v[12:13], off
	global_load_dword v134, v[14:15], off offset:-4096
	global_load_dword v135, v[14:15], off
	global_load_dword v136, v[16:17], off offset:-4096
	global_load_dword v137, v[16:17], off
	v_addc_co_u32_e32 v19, vcc, 0, v1, vcc
	v_add_co_u32_e32 v20, vcc, s37, v0
	v_mov_b32_e32 v66, v64
	s_nop 0
	v_addc_co_u32_e32 v21, vcc, 0, v1, vcc
	v_mov_b32_e32 v67, v64
	v_mov_b32_e32 v76, v64
	v_mov_b32_e32 v77, v64
	v_mov_b32_e32 v78, v64
	v_mov_b32_e32 v79, v64
	v_mov_b32_e32 v72, v64
	v_mov_b32_e32 v73, v64
	v_mov_b32_e32 v74, v64
	v_mov_b32_e32 v75, v64
	v_mov_b32_e32 v68, v64
	v_mov_b32_e32 v69, v64
	v_mov_b32_e32 v70, v64
	v_mov_b32_e32 v71, v64
	v_mov_b32_e32 v60, v64
	v_mov_b32_e32 v61, v64
	v_mov_b32_e32 v62, v64
	v_mov_b32_e32 v63, v64
	v_mov_b32_e32 v56, v64
	v_mov_b32_e32 v57, v64
	v_mov_b32_e32 v58, v64
	v_mov_b32_e32 v59, v64
	v_mov_b32_e32 v52, v64
	v_mov_b32_e32 v53, v64
	v_mov_b32_e32 v54, v64
	v_mov_b32_e32 v55, v64
	v_mov_b32_e32 v48, v64
	v_mov_b32_e32 v49, v64
	v_mov_b32_e32 v50, v64
	s_waitcnt vmcnt(15)
	v_sub_u32_e32 v2, v3, v98
	v_min_i32_e32 v118, 0x80, v2
	v_cmp_lt_i32_e32 vcc, v160, v118
	v_mov_b32_e32 v51, v64
	v_mov_b32_e32 v28, v64
	v_cndmask_b32_e32 v2, 0, v160, vcc
	v_cmp_lt_i32_e32 vcc, v150, v118
	v_add_u32_e32 v2, v2, v117
	v_mov_b32_e32 v29, v64
	v_cndmask_b32_e32 v3, 0, v150, vcc
	v_cmp_lt_i32_e32 vcc, v151, v118
	v_add_u32_e32 v4, v3, v117
	v_ashrrev_i32_e32 v3, 31, v2
	v_cndmask_b32_e32 v5, 0, v151, vcc
	v_cmp_lt_i32_e32 vcc, v152, v118
	v_add_u32_e32 v6, v5, v117
	v_ashrrev_i32_e32 v5, 31, v4
	v_cndmask_b32_e32 v7, 0, v152, vcc
	v_add_co_u32_e32 v10, vcc, s38, v0
	v_add_u32_e32 v8, v7, v117
	s_nop 0
	v_addc_co_u32_e32 v11, vcc, 0, v1, vcc
	v_add_co_u32_e32 v12, vcc, s39, v0
	v_ashrrev_i32_e32 v7, 31, v6
	s_nop 0
	v_addc_co_u32_e32 v13, vcc, 0, v1, vcc
	global_load_dword v138, v[18:19], off offset:-4096
	global_load_dword v139, v[18:19], off
	global_load_dword v140, v[20:21], off offset:-4096
	global_load_dword v142, v[20:21], off
	global_load_dword v143, v[10:11], off offset:-4096
	global_load_dword v144, v[10:11], off
	global_load_dword v145, v[12:13], off offset:-4096
	global_load_dword v146, v[12:13], off
	v_add_co_u32_e32 v10, vcc, s40, v0
	v_lshlrev_b64 v[16:17], 10, v[2:3]
	s_nop 0
	v_addc_co_u32_e32 v11, vcc, 0, v1, vcc
	v_add_co_u32_e32 v12, vcc, s41, v0
	v_ashrrev_i32_e32 v9, 31, v8
	s_nop 0
	v_addc_co_u32_e32 v13, vcc, 0, v1, vcc
	v_add_co_u32_e32 v14, vcc, s42, v0
	v_lshlrev_b64 v[22:23], 10, v[4:5]
	s_nop 0
	v_addc_co_u32_e32 v15, vcc, 0, v1, vcc
	v_add_co_u32_e32 v18, vcc, s43, v0
	v_lshlrev_b64 v[24:25], 10, v[6:7]
	s_nop 0
	v_addc_co_u32_e32 v19, vcc, 0, v1, vcc
	v_add_co_u32_e32 v0, vcc, s44, v0
	v_lshl_add_u64 v[2:3], v[86:87], 0, v[16:17]
	s_nop 0
	v_addc_co_u32_e32 v1, vcc, 0, v1, vcc
	global_load_dword v147, v[10:11], off offset:-4096
	global_load_dword v153, v[10:11], off
	global_load_dword v154, v[12:13], off offset:-4096
	global_load_dword v155, v[12:13], off
	global_load_dword v156, v[14:15], off offset:-4096
	global_load_dword v157, v[14:15], off
	global_load_dword v158, v[18:19], off offset:-4096
	global_load_dword v159, v[18:19], off
	global_load_dword v170, v[0:1], off
	v_lshlrev_b64 v[18:19], 10, v[8:9]
	v_lshl_add_u64 v[4:5], v[86:87], 0, v[22:23]
	v_lshl_add_u64 v[6:7], v[86:87], 0, v[24:25]
	v_lshl_add_u64 v[0:1], v[86:87], 0, v[18:19]
	v_lshrrev_b32_e32 v46, 2, v149
	v_lshrrev_b32_e32 v35, 4, v46
	v_xor_b32_e32 v35, v35, v46
	v_and_b32_e32 v35, 7, v35
	v_lshlrev_b32_e32 v34, 4, v35
	v_mov_b32_e32 v35, 0
	v_sub_u32_e32 v38, v34, v124
	v_lshrrev_b32_e32 v46, 6, v46
	v_ashrrev_i32_e32 v39, 31, v38
	v_readfirstlane_b32 s100, v46
	s_lshl_b32 s100, s100, 10
	v_readfirstlane_b32 s98, v118
	s_lshr_b32 s99, s100, 11
	s_lshl_b32 s99, s99, 6
	s_sub_i32 s99, s98, s99
	s_max_i32 s99, s99, 0
	s_min_i32 s99, s99, 64
	s_add_i32 s99, s99, 15
	s_lshr_b32 s99, s99, 4
	v_readfirstlane_b32 s49, v237
	s_cmp_ge_u32 s49, 8
	s_cbranch_scc1 .Le2_rdy
	s_mov_b32 s50, 0
